# P5 head-loop top: vmcnt(0) -> vmcnt(8) so the 8 trailing A3 output stores stay in flight across the head boundary (in-order vmcnt still covers the LoRA DMA and raw k/v prefetch); on top of a1+a2+raw+p
# speedup vs baseline: 1.0076x; 1.0023x over previous
; #define LAS __attribute__((address_space(3)))
; #define LBAR() asm volatile("s_waitcnt lgkmcnt(0)\n\ts_barrier" ::: "memory")
; __device__ __forceinline__ void rwkv_chunk_group(Frame& F, int bc, unsigned long long& tsub) {
;     ...
;         asm volatile("s_waitcnt vmcnt(0)" ::: "memory"); LBAR();
;         f32x4 aw[2], aa[2], ag[2];
; #pragma unroll
;         for (int q = 0; q < 2; ++q) { const int n0 = 16 * ((2 * w + q) & 3); aw[q] = Z4; aa[q] = Z4; ag[q] = Z4;
;             const LAS unsigned char* wp = L + L_LWA + (n0 + fr) * 128 + fq * 16; const LAS unsigned char* gp = L + L_LG + (n0 + fr) * 64 + fq * 16;
; #pragma unroll
;             for (int k = 0; k < 2; ++k) { aw[q] = __builtin_amdgcn_mfma_f32_16x16x32_bf16(xw[k], *(const LAS bf16x8*)(wp + k * 64), aw[q], 0, 0, 0); aa[q] = __builtin_amdgcn_mfma_f32_16x16x32_bf16(xa[k], *(const LAS bf16x8*)(wp + 8192 + k * 64), aa[q], 0, 0, 0); }
; #pragma unroll
;             for (int k = 0; k < 5; ++k) ag[q] = __builtin_amdgcn_mfma_f32_16x16x32_bf16(xg[k], *(const LAS bf16x8*)(gp + k * 4096), ag[q], 0, 0, 0);
;         }
;         LBAR();
; #pragma unroll
;         for (int q = 0; q < 2; ++q) { const int tw = 2 * w + q, m0 = 16 * (tw >> 2), n0 = 16 * (tw & 3);
; #pragma unroll
;             for (int v = 0; v < 4; ++v) { const int t = m0 + 4 * fq + v, cc = n0 + fr;
;                 *(LAS float*)(L + L_WL + (t * 65 + cc) * 4) = aw[q][v]; *(LAS float*)(L + L_AL + (t * 65 + cc) * 4) = aa[q][v]; *(LAS float*)(L + L_GL + (t * 65 + cc) * 4) = ag[q][v]; } }
;         LBAR();
.LBB0_1412:
	s_waitcnt vmcnt(8)
	v_perm_b32 v160, v203, v202, s5
	v_perm_b32 v161, v216, v215, s5
	v_perm_b32 v166, v204, v203, s5
	v_perm_b32 v167, v217, v216, s5
	v_perm_b32 v168, v206, v205, s5
	v_perm_b32 v169, v219, v218, s5
	v_perm_b32 v170, v212, v207, s5
	v_perm_b32 v171, v221, v220, s5
	v_perm_b32 v165, v214, v213, s5
	v_perm_b32 v172, v223, v222, s5
	v_readlane_b32 s98, v254, 2
	v_readlane_b32 s100, v254, 20
	v_readlane_b32 s101, v254, 21
	s_add_i32 s98, s98, s12
	s_lshl_b32 s98, s98, 6
	s_and_b32 s98, s98, 0x1c0
	v_add_lshl_u32 v238, v208, s98, 2
	v_mov_b32_e32 v239, 0
	s_nop 0
	v_lshl_add_u64 v[232:233], s[100:101], 0, v[238:239]
	s_mov_b64 s[100:101], 0x2000
	v_lshl_add_u64 v[234:235], v[232:233], 0, s[100:101]
	s_mov_b64 s[100:101], 0x3800
	v_lshl_add_u64 v[236:237], v[232:233], 0, s[100:101]
	global_load_dword v224, v[232:233], off
	global_load_dword v225, v[232:233], off offset:2048
	global_load_dword v226, v[234:235], off offset:-4096
	global_load_dword v227, v[234:235], off
	global_load_dword v228, v[234:235], off offset:2048
	global_load_dword v229, v[236:237], off offset:-2048
	global_load_dword v230, v[236:237], off
	global_load_dword v231, v[236:237], off offset:2048
	s_waitcnt lgkmcnt(0)
	s_barrier
	ds_read_b128 v[36:39], v137
	ds_read_b128 v[44:47], v137 offset:64
	ds_read_b128 v[40:43], v137 offset:8192
	v_add_u32_e32 v52, s33, v111
	s_mov_b32 s68, s12
	s_waitcnt lgkmcnt(2)
	v_mfma_f32_16x16x32_bf16 v[36:39], v[0:3], v[36:39], 0
	v_readlane_b32 s12, v254, 2
	s_add_i32 s14, s68, s12
	s_lshl_b32 s14, s14, 6
	s_waitcnt lgkmcnt(1)
	v_mfma_f32_16x16x32_bf16 v[36:39], v[4:7], v[44:47], v[36:39]
	ds_read_b128 v[44:47], v137 offset:8256
	s_and_b32 s14, s14, 0x1c0
	s_add_i32 s66, s11, s14
	s_waitcnt lgkmcnt(1)
	v_mfma_f32_16x16x32_bf16 v[40:43], v[8:11], v[40:43], 0
	ds_read_b128 v[76:79], v138 offset:4096
	v_add_u32_e32 v191, s6, v125
	v_readlane_b32 s13, v254, 3
	s_waitcnt lgkmcnt(1)
	v_mfma_f32_16x16x32_bf16 v[40:43], v[12:15], v[44:47], v[40:43]
	ds_read_b128 v[44:47], v138
	s_mov_b32 s64, s12
	s_add_i32 s12, s68, 1
	s_waitcnt lgkmcnt(0)
	v_mfma_f32_16x16x32_bf16 v[44:47], v[16:19], v[44:47], 0
	ds_read_b128 v[84:87], v139 offset:64
	s_add_i32 s13, s12, s64
	v_add_u32_e32 v96, s6, v124
	v_mfma_f32_16x16x32_bf16 v[44:47], v[20:23], v[76:79], v[44:47]
	ds_read_b128 v[76:79], v138 offset:8192
	ds_read_b128 v[80:83], v139 offset:8192
	v_add_u32_e32 v93, s7, v123
	s_waitcnt lgkmcnt(1)
	v_mfma_f32_16x16x32_bf16 v[44:47], v[24:27], v[76:79], v[44:47]
	ds_read_b128 v[76:79], v138 offset:12288
	ds_read_b128 v[88:91], v140 offset:4096
	v_add_u32_e32 v97, s7, v124
	s_waitcnt lgkmcnt(1)
	v_mfma_f32_16x16x32_bf16 v[44:47], v[28:31], v[76:79], v[44:47]
	ds_read_b128 v[76:79], v138 offset:16384
	v_add_u32_e32 v192, s7, v125
	v_lshlrev_b32_e32 v197, 16, v162
	s_waitcnt lgkmcnt(0)
	v_mfma_f32_16x16x32_bf16 v[44:47], v[32:35], v[76:79], v[44:47]
	ds_read_b128 v[76:79], v139
	v_and_b32_e32 v199, 0xffff0000, v172
	s_ashr_i32 s67, s66, 31
	s_waitcnt lgkmcnt(0)
	v_mfma_f32_16x16x32_bf16 v[76:79], v[0:3], v[76:79], 0
	s_and_b32 s13, s13, 7
	v_mfma_f32_16x16x32_bf16 v[76:79], v[4:7], v[84:87], v[76:79]
	ds_read_b128 v[84:87], v139 offset:8256
	v_mfma_f32_16x16x32_bf16 v[80:83], v[8:11], v[80:83], 0
	s_waitcnt lgkmcnt(0)
	v_mfma_f32_16x16x32_bf16 v[80:83], v[12:15], v[84:87], v[80:83]
	ds_read_b128 v[84:87], v140
	s_waitcnt lgkmcnt(0)
	v_mfma_f32_16x16x32_bf16 v[84:87], v[16:19], v[84:87], 0
	v_mfma_f32_16x16x32_bf16 v[84:87], v[20:23], v[88:91], v[84:87]
	ds_read_b128 v[88:91], v140 offset:8192
	s_waitcnt lgkmcnt(0)
	v_mfma_f32_16x16x32_bf16 v[84:87], v[24:27], v[88:91], v[84:87]
	ds_read_b128 v[88:91], v140 offset:12288
	s_waitcnt lgkmcnt(0)
	v_mfma_f32_16x16x32_bf16 v[84:87], v[28:31], v[88:91], v[84:87]
	ds_read_b128 v[88:91], v140 offset:16384
	s_waitcnt lgkmcnt(0)
	s_barrier
	ds_write_b32 v52, v36
	v_add_u32_e32 v36, s6, v111
	ds_write_b32 v36, v40
	v_add_u32_e32 v36, s7, v111
	ds_write_b32 v36, v44
	v_add_u32_e32 v36, s33, v112
	ds_write_b32 v36, v37
	v_add_u32_e32 v36, s6, v112
	ds_write_b32 v36, v41
	v_add_u32_e32 v36, s7, v112
	ds_write_b32 v36, v45
	v_add_u32_e32 v36, s33, v113
	ds_write_b32 v36, v38
	v_add_u32_e32 v36, s6, v113
	ds_write_b32 v36, v42
	v_add_u32_e32 v36, s7, v113
	ds_write_b32 v36, v46
	v_add_u32_e32 v36, s33, v114
	ds_write_b32 v36, v39
	v_add_u32_e32 v36, s6, v114
	s_waitcnt lgkmcnt(10)
	v_mfma_f32_16x16x32_bf16 v[84:87], v[32:35], v[88:91], v[84:87]
	ds_write_b32 v36, v43
	v_add_u32_e32 v36, s7, v114
	ds_write_b32 v36, v47
	v_add_u32_e32 v36, s33, v115
	ds_write_b32 v36, v76
	v_add_u32_e32 v36, s6, v115
	ds_write_b32 v36, v80
	v_add_u32_e32 v36, s7, v115
	ds_write_b32 v36, v84
	v_add_u32_e32 v36, s33, v116
	ds_write_b32 v36, v77
	v_add_u32_e32 v36, s6, v116
	ds_write_b32 v36, v81
	v_add_u32_e32 v36, s7, v116
	ds_write_b32 v36, v85
	v_add_u32_e32 v36, s33, v117
	ds_write_b32 v36, v78
	v_add_u32_e32 v36, s6, v117
	ds_write_b32 v36, v82
	v_add_u32_e32 v36, s7, v117
	ds_write_b32 v36, v86
	v_add_u32_e32 v36, s33, v118
	ds_write_b32 v36, v79
	v_add_u32_e32 v36, s6, v118
	ds_write_b32 v36, v83
	v_add_u32_e32 v36, s7, v118
	ds_write_b32 v36, v87
	v_add_u32_e32 v36, s14, v208
	v_ashrrev_i32_e32 v37, 31, v36
	v_readlane_b32 s14, v254, 20
	v_lshlrev_b64 v[36:37], 2, v[36:37]
	v_readlane_b32 s15, v254, 21
	s_waitcnt lgkmcnt(0)
	s_barrier
; #define LAS __attribute__((address_space(3)))
; __device__ __forceinline__ float sigmoidf_(float x) { return __builtin_amdgcn_rcpf(1.0f + __expf(-x)); }
; __device__ __forceinline__ void rwkv_chunk_group(Frame& F, int bc, unsigned long long& tsub) {
;     ...
;         const int gc = h * 64 + ch;
;         const float mur = mu[gc], muk = mu[512 + gc], muv = mu[1024 + gc];
;         const float w0 = (PRM + 2048)[gc], a0 = (PRM + 2560)[gc], k_k = (PRM + 3072)[gc], k_a = (PRM + 3584)[gc], r_k = (PRM + 4096)[gc];
;         float rr[8], kp[8], vv[8], aa[8], bb[8], ld[8], vbv[8], ggv[8];
;         float pr = bf2f(raw[0][0]), pk = bf2f(raw[0][1]), pv = bf2f(raw[0][2]);
;         bf16* VBp = (bf16*)(F.ws + WS_VB) + (size_t)item * 4096; bf16* Gp = (bf16*)(F.ws + WS_G) + (size_t)item * 4096;
;         float run = 0.f; float kkv[8], icv[8], sq[8], bq[8];
; #pragma unroll
;         for (int tt = 0; tt < 8; ++tt) { const int t = tb + tt;
;             const float cr = bf2f(raw[tt + 1][0]), ck = bf2f(raw[tt + 1][1]), cv = bf2f(raw[tt + 1][2]);
;             const float r = cr + (pr - cr) * mur, k = ck + (pk - ck) * muk, v = cv + (pv - cv) * muv; pr = cr; pk = ck; pv = cv;
;             const float wl = *(const LAS float*)(L + L_WL + (t * 65 + ch) * 4), al = *(const LAS float*)(L + L_AL + (t * 65 + ch) * 4), gl = *(const LAS float*)(L + L_GL + (t * 65 + ch) * 4);
;             const float z = -(w0 + wl); const float sp = fmaxf(z, 0.f) + __logf(1.f + __expf(-fabsf(z)));
;             const float lgd = -__expf(-sp - 0.5f);
;             const float ic = sigmoidf_(a0 + al);
;             const float kv = k * k_k; const float kq = k * (1.f + (ic - 1.f) * k_a);
;             kkv[tt] = kv; icv[tt] = ic; sq[tt] = kv * kv; bq[tt] = r * kq * r_k;
;             rr[tt] = r; kp[tt] = kq; vv[tt] = v; run += lgd; ld[tt] = run; ggv[tt] = gl;
;         }
	v_add_u32_e32 v41, s7, v120
	v_add_u32_e32 v87, s7, v122
	v_lshl_add_u64 v[38:39], s[14:15], 0, v[36:37]
	s_waitcnt vmcnt(0)
	v_mov_b32_e32 v95, v224
	v_mov_b32_e32 v42, v225
	s_movk_i32 s14, 0x1000
	v_add_co_u32_e32 v38, vcc, s14, v38
	v_readlane_b32 s14, v254, 29
	s_nop 0
	v_addc_co_u32_e32 v39, vcc, 0, v39, vcc
	v_readlane_b32 s15, v254, 30
	v_mov_b32_e32 v52, v226
	v_add_u32_e32 v83, s7, v121
	v_lshl_add_u64 v[38:39], s[14:15], 0, v[36:37]
	v_mov_b32_e32 v45, v227
	v_readlane_b32 s14, v254, 31
	v_readlane_b32 s15, v254, 32
	v_lshlrev_b32_e32 v82, 16, v155
	v_and_b32_e32 v77, 0xffff0000, v167
	v_lshl_add_u64 v[38:39], s[14:15], 0, v[36:37]
	v_mov_b32_e32 v43, v228
	v_readlane_b32 s14, v254, 33
	v_readlane_b32 s15, v254, 34
	v_lshlrev_b32_e32 v76, 16, v167
	v_and_b32_e32 v79, 0xffff0000, v166
	v_lshl_add_u64 v[38:39], s[14:15], 0, v[36:37]
	v_readlane_b32 s14, v254, 35
	v_readlane_b32 s15, v254, 36
	v_mov_b32_e32 v44, v229
	v_lshlrev_b32_e32 v78, 16, v166
	v_lshl_add_u64 v[38:39], s[14:15], 0, v[36:37]
	v_mov_b32_e32 v46, v230
	v_readlane_b32 s14, v254, 37
	v_readlane_b32 s15, v254, 38
	v_lshlrev_b32_e32 v86, 16, v157
	v_and_b32_e32 v91, 0xffff0000, v168
	v_lshl_add_u64 v[36:37], s[14:15], 0, v[36:37]
	v_mov_b32_e32 v103, v231
	v_lshlrev_b32_e32 v36, 16, v153
	v_lshlrev_b32_e32 v37, 16, v154
	v_sub_f32_e32 v36, v36, v37
	v_add_u32_e32 v38, s6, v119
	v_add_u32_e32 v39, s7, v119
	ds_read_b32 v38, v38
	ds_read_b32 v47, v39
	ds_read_b32 v177, v41
	ds_read_b32 v185, v87
	ds_read_b32 v191, v191
	v_lshlrev_b32_e32 v90, 16, v168
	v_and_b32_e32 v85, 0xffff0000, v169
	ds_read_b32 v182, v83
	ds_read_b32 v96, v96
	ds_read_b32 v189, v93
	ds_read_b32 v193, v97
	ds_read_b32 v194, v192
	s_waitcnt vmcnt(7)
	v_fma_f32 v173, v36, v95, v37
	v_add_u32_e32 v36, s33, v119
	ds_read_b32 v36, v36
	s_waitcnt vmcnt(4) lgkmcnt(0)
	v_add_f32_e32 v36, v45, v36
	v_max_f32_e64 v39, -v36, 0
	v_mul_f32_e64 v36, |v36|, s1
	v_exp_f32_e32 v36, v36
	s_nop 0
	v_add_f32_e32 v36, 1.0, v36
	v_cmp_gt_f32_e32 vcc, s8, v36
	s_nop 1
	v_cndmask_b32_e64 v40, 0, 32, vcc
	v_ldexp_f32 v36, v36, v40
	v_log_f32_e32 v36, v36
	s_nop 0
	v_mul_f32_e32 v40, 0x3f317217, v36
	v_fma_f32 v40, v36, s9, -v40
	v_fmac_f32_e32 v40, 0x3377d1cf, v36
	v_fmac_f32_e32 v40, 0x3f317217, v36
	v_cmp_lt_f32_e64 s[64:65], |v36|, s10
	s_nop 1
	v_cndmask_b32_e64 v36, v36, v40, s[64:65]
	v_cndmask_b32_e32 v40, 0, v147, vcc
	v_sub_f32_e32 v36, v36, v40
	v_add_f32_e32 v36, v39, v36
	v_add_u32_e32 v39, s33, v120
	ds_read_b32 v39, v39
	v_sub_f32_e32 v36, -0.5, v36
	v_mul_f32_e32 v36, 0x3fb8aa3b, v36
	v_exp_f32_e32 v102, v36
	s_waitcnt vmcnt(3)
	v_add_f32_e32 v36, v43, v38
	v_mul_f32_e32 v36, 0xbfb8aa3b, v36
	v_add_u32_e32 v40, s6, v120
	v_exp_f32_e32 v36, v36
	ds_read_b32 v40, v40
	s_waitcnt lgkmcnt(1)
	v_add_f32_e32 v39, v45, v39
	v_max_f32_e64 v41, -v39, 0
	v_mul_f32_e64 v39, |v39|, s1
	v_exp_f32_e32 v39, v39
	v_add_f32_e32 v36, 1.0, v36
	v_rcp_f32_e32 v38, v36
	v_sub_f32_e32 v36, v37, v82
	v_fma_f32 v174, v36, v95, v82
	v_and_b32_e32 v37, 0xffff0000, v161
	v_lshlrev_b32_e32 v36, 16, v161
	v_add_f32_e32 v39, 1.0, v39
	v_pk_add_f32 v[36:37], v[36:37], v[76:77] neg_lo:[0,1] neg_hi:[0,1]
	v_cmp_gt_f32_e32 vcc, s8, v39
	v_pk_fma_f32 v[36:37], v[36:37], v[52:53], v[76:77] op_sel_hi:[1,0,1]
	s_nop 0
	v_cndmask_b32_e64 v76, 0, 32, vcc
	v_ldexp_f32 v39, v39, v76
	v_log_f32_e32 v39, v39
	s_nop 0
	v_mul_f32_e32 v76, 0x3f317217, v39
	v_fma_f32 v76, v39, s9, -v76
	v_fmac_f32_e32 v76, 0x3377d1cf, v39
	v_fmac_f32_e32 v76, 0x3f317217, v39
	v_cmp_lt_f32_e64 s[64:65], |v39|, s10
	s_nop 1
	v_cndmask_b32_e64 v39, v39, v76, s[64:65]
	v_cndmask_b32_e32 v76, 0, v147, vcc
	v_sub_f32_e32 v39, v39, v76
	v_add_f32_e32 v39, v41, v39
	v_sub_f32_e32 v39, -0.5, v39
	v_mul_f32_e32 v39, 0x3fb8aa3b, v39
	v_exp_f32_e32 v76, v39
	s_waitcnt lgkmcnt(0)
	v_add_f32_e32 v39, v43, v40
	v_mul_f32_e32 v39, 0xbfb8aa3b, v39
	v_exp_f32_e32 v39, v39
	v_and_b32_e32 v41, 0xffff0000, v160
	v_lshlrev_b32_e32 v40, 16, v160
	v_pk_add_f32 v[40:41], v[40:41], v[78:79] neg_lo:[0,1] neg_hi:[0,1]
	v_add_f32_e32 v39, 1.0, v39
	v_rcp_f32_e32 v39, v39
	v_pk_fma_f32 v[80:81], v[40:41], v[42:43], v[78:79] op_sel_hi:[1,0,1]
	v_sub_f32_e64 v176, -v102, v76
	v_lshlrev_b32_e32 v76, 16, v156
	v_pk_add_f32 v[40:41], v[38:39], -1.0 op_sel_hi:[1,0]
	s_waitcnt vmcnt(1)
	v_pk_fma_f32 v[40:41], v[46:47], v[40:41], 1.0 op_sel_hi:[0,1,0]
	v_pk_mul_f32 v[40:41], v[80:81], v[40:41]
	s_nop 0
	v_mul_f32_e32 v78, v173, v40
	s_waitcnt vmcnt(0)
	v_mul_f32_e32 v101, v103, v78
	v_mul_f32_e32 v78, v174, v41
	v_mul_f32_e32 v100, v103, v78
	v_sub_f32_e32 v78, v82, v76
	v_fma_f32 v175, v78, v95, v76
	v_add_u32_e32 v78, s33, v121
	ds_read_b32 v78, v78
	v_add_u32_e32 v82, s6, v121
	ds_read_b32 v82, v82
	v_sub_f32_e32 v76, v76, v86
	v_fma_f32 v178, v76, v95, v86
	s_waitcnt lgkmcnt(1)
	v_add_f32_e32 v78, v45, v78
	v_max_f32_e64 v83, -v78, 0
	v_mul_f32_e64 v78, |v78|, s1
	v_exp_f32_e32 v78, v78
	s_waitcnt lgkmcnt(0)
	v_add_f32_e32 v82, v43, v82
	v_mul_f32_e32 v82, 0xbfb8aa3b, v82
	v_exp_f32_e32 v82, v82
	v_add_f32_e32 v78, 1.0, v78
	v_cmp_gt_f32_e32 vcc, s8, v78
	v_add_f32_e32 v82, 1.0, v82
	s_nop 0
	v_cndmask_b32_e64 v84, 0, 32, vcc
	v_ldexp_f32 v78, v78, v84
	v_log_f32_e32 v78, v78
	v_rcp_f32_e32 v82, v82
	v_mul_f32_e32 v84, 0x3f317217, v78
	v_fma_f32 v84, v78, s9, -v84
	v_fmac_f32_e32 v84, 0x3377d1cf, v78
	v_fmac_f32_e32 v84, 0x3f317217, v78
	v_cmp_lt_f32_e64 s[64:65], |v78|, s10
	s_nop 1
	v_cndmask_b32_e64 v78, v78, v84, s[64:65]
	v_cndmask_b32_e32 v84, 0, v147, vcc
	v_sub_f32_e32 v78, v78, v84
	v_add_f32_e32 v78, v83, v78
	v_sub_f32_e32 v78, -0.5, v78
	v_mul_f32_e32 v78, 0x3fb8aa3b, v78
	v_exp_f32_e32 v78, v78
	v_add_u32_e32 v83, s6, v122
	ds_read_b32 v83, v83
	v_lshlrev_b32_e32 v84, 16, v169
	v_sub_f32_e32 v179, v176, v78
	v_add_u32_e32 v78, s33, v122
	ds_read_b32 v78, v78
	v_pk_mov_b32 v[76:77], v[76:77], v[84:85] op_sel:[1,0]
	s_waitcnt lgkmcnt(0)
; #define LAS __attribute__((address_space(3)))
; __device__ __forceinline__ float sigmoidf_(float x) { return __builtin_amdgcn_rcpf(1.0f + __expf(-x)); }
; __device__ __forceinline__ void rwkv_chunk_group(Frame& F, int bc, unsigned long long& tsub) {
;     ...
;         for (int tt = 0; tt < 8; ++tt) { const int t = tb + tt;
;             const float cr = bf2f(raw[tt + 1][0]), ck = bf2f(raw[tt + 1][1]), cv = bf2f(raw[tt + 1][2]);
;             const float r = cr + (pr - cr) * mur, k = ck + (pk - ck) * muk, v = cv + (pv - cv) * muv; pr = cr; pk = ck; pv = cv;
;             const float wl = *(const LAS float*)(L + L_WL + (t * 65 + ch) * 4), al = *(const LAS float*)(L + L_AL + (t * 65 + ch) * 4), gl = *(const LAS float*)(L + L_GL + (t * 65 + ch) * 4);
;             const float z = -(w0 + wl); const float sp = fmaxf(z, 0.f) + __logf(1.f + __expf(-fabsf(z)));
;             const float lgd = -__expf(-sp - 0.5f);
;             const float ic = sigmoidf_(a0 + al);
;             const float kv = k * k_k; const float kq = k * (1.f + (ic - 1.f) * k_a);
;             kkv[tt] = kv; icv[tt] = ic; sq[tt] = kv * kv; bq[tt] = r * kq * r_k;
;             rr[tt] = r; kp[tt] = kq; vv[tt] = v; run += lgd; ld[tt] = run; ggv[tt] = gl;
;         }
	v_add_f32_e32 v78, v45, v78
	v_max_f32_e64 v87, -v78, 0
	v_mul_f32_e64 v78, |v78|, s1
	v_exp_f32_e32 v78, v78
	v_pk_add_f32 v[76:77], v[76:77], v[84:85] neg_lo:[0,1] neg_hi:[0,1]
	v_add_f32_e32 v78, 1.0, v78
	v_cmp_gt_f32_e32 vcc, s8, v78
	v_pk_fma_f32 v[76:77], v[76:77], v[52:53], v[84:85] op_sel_hi:[1,0,1]
	s_nop 0
	v_cndmask_b32_e64 v88, 0, 32, vcc
	v_ldexp_f32 v78, v78, v88
	v_log_f32_e32 v78, v78
	s_nop 0
	v_mul_f32_e32 v88, 0x3f317217, v78
	v_fma_f32 v88, v78, s9, -v88
	v_fmac_f32_e32 v88, 0x3377d1cf, v78
	v_fmac_f32_e32 v88, 0x3f317217, v78
	v_cmp_lt_f32_e64 s[64:65], |v78|, s10
	s_nop 1
	v_cndmask_b32_e64 v78, v78, v88, s[64:65]
	v_cndmask_b32_e32 v88, 0, v147, vcc
	v_sub_f32_e32 v78, v78, v88
	v_add_f32_e32 v78, v87, v78
	v_sub_f32_e32 v78, -0.5, v78
	v_mul_f32_e32 v78, 0x3fb8aa3b, v78
	v_exp_f32_e32 v87, v78
	v_add_f32_e32 v78, v43, v83
	v_mul_f32_e32 v78, 0xbfb8aa3b, v78
	v_exp_f32_e32 v78, v78
	v_sub_f32_e32 v181, v179, v87
	v_lshlrev_b32_e32 v87, 16, v158
	v_sub_f32_e32 v86, v86, v87
	v_add_f32_e32 v78, 1.0, v78
	v_rcp_f32_e32 v83, v78
	v_pk_mov_b32 v[78:79], v[78:79], v[90:91] op_sel:[1,0]
	v_fma_f32 v180, v86, v95, v87
	v_pk_add_f32 v[78:79], v[78:79], v[90:91] neg_lo:[0,1] neg_hi:[0,1]
	v_add_u32_e32 v86, s33, v123
	v_pk_fma_f32 v[88:89], v[78:79], v[42:43], v[90:91] op_sel_hi:[1,0,1]
	v_pk_add_f32 v[78:79], v[82:83], -1.0 op_sel_hi:[1,0]
	ds_read_b32 v86, v86
	v_pk_fma_f32 v[78:79], v[46:47], v[78:79], 1.0 op_sel_hi:[0,1,0]
	v_pk_mul_f32 v[78:79], v[88:89], v[78:79]
	s_nop 0
	v_mul_f32_e32 v92, v175, v78
	v_mul_f32_e32 v187, v103, v92
	v_mul_f32_e32 v92, v178, v79
	v_mul_f32_e32 v186, v103, v92
	v_add_u32_e32 v92, s6, v123
	ds_read_b32 v92, v92
	s_waitcnt lgkmcnt(1)
	v_add_f32_e32 v86, v45, v86
	v_max_f32_e64 v93, -v86, 0
	v_mul_f32_e64 v86, |v86|, s1
	v_exp_f32_e32 v86, v86
	s_nop 0
	v_add_f32_e32 v86, 1.0, v86
	v_cmp_gt_f32_e32 vcc, s8, v86
	s_nop 1
	v_cndmask_b32_e64 v94, 0, 32, vcc
	v_ldexp_f32 v86, v86, v94
	v_log_f32_e32 v86, v86
	s_nop 0
	v_mul_f32_e32 v94, 0x3f317217, v86
	v_fma_f32 v94, v86, s9, -v94
	v_fmac_f32_e32 v94, 0x3377d1cf, v86
	v_fmac_f32_e32 v94, 0x3f317217, v86
	v_cmp_lt_f32_e64 s[64:65], |v86|, s10
	s_nop 1
	v_cndmask_b32_e64 v86, v86, v94, s[64:65]
	v_cndmask_b32_e32 v94, 0, v147, vcc
	v_sub_f32_e32 v86, v86, v94
	v_lshlrev_b32_e32 v94, 16, v159
	v_sub_f32_e32 v87, v87, v94
	v_fma_f32 v183, v87, v95, v94
	v_add_u32_e32 v87, s33, v124
	ds_read_b32 v87, v87
	v_add_f32_e32 v86, v93, v86
	v_sub_f32_e32 v86, -0.5, v86
	v_mul_f32_e32 v86, 0x3fb8aa3b, v86
	v_exp_f32_e32 v93, v86
	s_waitcnt lgkmcnt(0)
	v_add_f32_e32 v87, v45, v87
	v_max_f32_e64 v97, -v87, 0
	v_mul_f32_e64 v87, |v87|, s1
	v_exp_f32_e32 v87, v87
	v_add_f32_e32 v86, v43, v92
	v_mul_f32_e32 v86, 0xbfb8aa3b, v86
	v_exp_f32_e32 v86, v86
	v_add_f32_e32 v87, 1.0, v87
	v_cmp_gt_f32_e32 vcc, s8, v87
	v_sub_f32_e32 v184, v181, v93
	v_add_f32_e32 v86, 1.0, v86
	v_cndmask_b32_e64 v98, 0, 32, vcc
	v_ldexp_f32 v87, v87, v98
	v_log_f32_e32 v87, v87
	v_rcp_f32_e32 v86, v86
	v_sub_f32_e32 v94, v94, v197
	v_and_b32_e32 v93, 0xffff0000, v171
	v_mul_f32_e32 v98, 0x3f317217, v87
	v_fma_f32 v98, v87, s9, -v98
	v_fmac_f32_e32 v98, 0x3377d1cf, v87
	v_fmac_f32_e32 v98, 0x3f317217, v87
	v_cmp_lt_f32_e64 s[64:65], |v87|, s10
	v_lshlrev_b32_e32 v92, 16, v171
	v_pk_mov_b32 v[84:85], v[84:85], v[92:93] op_sel:[1,0]
	v_cndmask_b32_e64 v87, v87, v98, s[64:65]
	v_cndmask_b32_e32 v98, 0, v147, vcc
	v_sub_f32_e32 v87, v87, v98
	v_add_f32_e32 v87, v97, v87
	v_sub_f32_e32 v87, -0.5, v87
	v_mul_f32_e32 v87, 0x3fb8aa3b, v87
	v_exp_f32_e32 v188, v87
	v_add_f32_e32 v87, v43, v96
	v_mul_f32_e32 v87, 0xbfb8aa3b, v87
	v_exp_f32_e32 v87, v87
	v_and_b32_e32 v97, 0xffff0000, v170
	v_lshlrev_b32_e32 v96, 16, v170
	v_pk_mov_b32 v[90:91], v[90:91], v[96:97] op_sel:[1,0]
	v_add_f32_e32 v87, 1.0, v87
	v_rcp_f32_e32 v87, v87
	v_pk_add_f32 v[90:91], v[90:91], v[96:97] neg_lo:[0,1] neg_hi:[0,1]
	v_pk_add_f32 v[84:85], v[84:85], v[92:93] neg_lo:[0,1] neg_hi:[0,1]
	v_pk_fma_f32 v[98:99], v[90:91], v[42:43], v[96:97] op_sel_hi:[1,0,1]
	v_pk_add_f32 v[90:91], v[86:87], -1.0 op_sel_hi:[1,0]
	v_pk_fma_f32 v[84:85], v[84:85], v[52:53], v[92:93] op_sel_hi:[1,0,1]
	v_pk_fma_f32 v[90:91], v[46:47], v[90:91], 1.0 op_sel_hi:[0,1,0]
	v_pk_mul_f32 v[90:91], v[98:99], v[90:91]
	s_nop 0
	v_mul_f32_e32 v190, v180, v90
	v_mul_f32_e32 v196, v103, v190
	v_mul_f32_e32 v190, v183, v91
	v_mul_f32_e32 v195, v103, v190
	v_sub_f32_e32 v190, v184, v188
	v_fma_f32 v188, v94, v95, v197
	v_add_u32_e32 v94, s33, v125
	ds_read_b32 v94, v94
	v_permlane32_swap_b32_e32 v101, v196
	v_permlane32_swap_b32_e32 v100, v195
	s_waitcnt lgkmcnt(0)
	v_add_f32_e32 v94, v45, v94
	v_max_f32_e64 v192, -v94, 0
	v_mul_f32_e64 v94, |v94|, s1
	v_exp_f32_e32 v94, v94
	v_add_f32_e32 v201, v101, v196
	v_add_f32_e32 v195, v100, v195
	v_add_f32_e32 v94, 1.0, v94
	v_cmp_gt_f32_e32 vcc, s8, v94
	s_nop 1
	v_cndmask_b32_e64 v198, 0, 32, vcc
	v_ldexp_f32 v94, v94, v198
	v_log_f32_e32 v94, v94
	s_nop 0
	v_mul_f32_e32 v198, 0x3f317217, v94
	v_fma_f32 v198, v94, s9, -v198
	v_fmac_f32_e32 v198, 0x3377d1cf, v94
	v_fmac_f32_e32 v198, 0x3f317217, v94
	v_cmp_lt_f32_e64 s[64:65], |v94|, s10
	s_nop 1
	v_cndmask_b32_e64 v94, v94, v198, s[64:65]
	v_cndmask_b32_e32 v198, 0, v147, vcc
	v_sub_f32_e32 v94, v94, v198
	v_lshlrev_b32_e32 v198, 16, v172
	v_pk_mov_b32 v[92:93], v[92:93], v[198:199] op_sel:[1,0]
	v_add_f32_e32 v94, v192, v94
	v_pk_add_f32 v[92:93], v[92:93], v[198:199] neg_lo:[0,1] neg_hi:[0,1]
	v_sub_f32_e32 v94, -0.5, v94
	v_pk_fma_f32 v[92:93], v[92:93], v[52:53], v[198:199] op_sel_hi:[1,0,1]
	v_add_u32_e32 v52, s33, v126
	ds_read_b32 v52, v52
	v_mul_f32_e32 v94, 0x3fb8aa3b, v94
	v_exp_f32_e32 v192, v94
	v_add_f32_e32 v94, v43, v191
	v_lshlrev_b32_e32 v191, 16, v163
	v_sub_f32_e32 v197, v197, v191
	v_fmac_f32_e32 v191, v197, v95
	v_add_u32_e32 v95, s6, v126
	v_add_u32_e32 v197, s7, v126
	ds_read_b32 v95, v95
	ds_read_b32 v200, v197
	s_waitcnt lgkmcnt(2)
; #define GAS __attribute__((address_space(1)))
; #define LAS __attribute__((address_space(3)))
; __device__ __forceinline__ unsigned pk2(float lo, float hi) { f32x2_k v = {lo, hi}; bf16x2_k b = __builtin_convertvector(v, bf16x2_k); return __builtin_bit_cast(unsigned, b); }
; __device__ __forceinline__ void rwkv_chunk_group(Frame& F, int bc, unsigned long long& tsub) {
;     ...
;         wave_sum8(sq); wave_sum8(bq);
; #pragma unroll
;         for (int tt = 0; tt < 8; ++tt) { const float kn = kkv[tt] * __builtin_amdgcn_rsqf(fmaxf(sq[tt], 1e-24f));
;             aa[tt] = -kn; bb[tt] = kn * icv[tt]; vbv[tt] = bq[tt] * vv[tt]; }
;         *(LAS float*)(L + L_GT + (w * 64 + ch) * 4) = run;
;         *(GAS v4u*)(VBp + ch * 64 + tb) = (v4u){pk2(vbv[0], vbv[1]), pk2(vbv[2], vbv[3]), pk2(vbv[4], vbv[5]), pk2(vbv[6], vbv[7])};
;         *(GAS v4u*)(Gp + ch * 64 + tb) = (v4u){pk2(ggv[0], ggv[1]), pk2(ggv[2], ggv[3]), pk2(ggv[4], ggv[5]), pk2(ggv[6], ggv[7])};
;         if (hh + 1 < RW_H) {
;             const bool has = (c * CH + tb > 0);
; #pragma unroll
;             for (int tt = 0; tt < 9; ++tt) { const size_t off = (size_t)(row0 + tb + tt - 1) * PRW + hnext * 64 + ch;
;                 if (tt > 0 || has) { raw[tt][0] = P[off]; raw[tt][1] = P[off + 512]; raw[tt][2] = P[off + 1024]; } }
	v_add_f32_e32 v45, v45, v52
	v_max_f32_e64 v52, -v45, 0
	v_mul_f32_e64 v45, |v45|, s1
	v_exp_f32_e32 v45, v45
	s_waitcnt lgkmcnt(1)
	v_add_f32_e32 v43, v43, v95
	v_mul_f32_e32 v94, 0xbfb8aa3b, v94
	v_mul_f32_e32 v43, 0xbfb8aa3b, v43
	v_add_f32_e32 v45, 1.0, v45
	v_cmp_gt_f32_e32 vcc, s8, v45
	v_exp_f32_e32 v94, v94
	v_exp_f32_e32 v43, v43
	v_cndmask_b32_e64 v197, 0, 32, vcc
	v_ldexp_f32 v45, v45, v197
	v_log_f32_e32 v45, v45
	v_add_f32_e32 v94, 1.0, v94
	v_add_f32_e32 v43, 1.0, v43
	v_rcp_f32_e32 v94, v94
	v_mul_f32_e32 v197, 0x3f317217, v45
	v_fma_f32 v197, v45, s9, -v197
	v_fmac_f32_e32 v197, 0x3377d1cf, v45
	v_fmac_f32_e32 v197, 0x3f317217, v45
	v_cmp_lt_f32_e64 s[64:65], |v45|, s10
	v_rcp_f32_e32 v95, v43
	v_sub_f32_e32 v192, v190, v192
	v_cndmask_b32_e64 v45, v45, v197, s[64:65]
	v_cndmask_b32_e32 v197, 0, v147, vcc
	v_sub_f32_e32 v45, v45, v197
	v_add_f32_e32 v45, v52, v45
	v_sub_f32_e32 v45, -0.5, v45
	v_mul_f32_e32 v45, 0x3fb8aa3b, v45
	v_exp_f32_e32 v45, v45
	s_nop 0
	v_pk_mul_f32 v[100:101], v[80:81], v[44:45] op_sel_hi:[1,0]
	v_pk_mul_f32 v[80:81], v[98:99], v[44:45] op_sel_hi:[1,0]
	v_pk_mul_f32 v[196:197], v[100:101], v[100:101]
	v_pk_mul_f32 v[98:99], v[80:81], v[80:81]
	v_sub_f32_e32 v52, v192, v45
	s_nop 0
	v_permlane32_swap_b32_e32 v196, v98
	v_permlane32_swap_b32_e32 v197, v99
	v_add_f32_e32 v196, v196, v98
	v_add_f32_e32 v197, v197, v99
	v_lshlrev_b32_e32 v98, 16, v165
	v_and_b32_e32 v99, 0xffff0000, v165
	v_pk_mov_b32 v[96:97], v[96:97], v[98:99] op_sel:[1,0]
	v_pk_mul_f32 v[88:89], v[88:89], v[44:45] op_sel_hi:[1,0]
	v_pk_add_f32 v[96:97], v[96:97], v[98:99] neg_lo:[0,1] neg_hi:[0,1]
	v_pk_mul_f32 v[198:199], v[88:89], v[88:89]
	v_pk_fma_f32 v[42:43], v[96:97], v[42:43], v[98:99] op_sel_hi:[1,0,1]
	v_pk_add_f32 v[98:99], v[94:95], -1.0 op_sel_hi:[1,0]
	v_pk_mul_f32 v[44:45], v[42:43], v[44:45] op_sel_hi:[1,0]
	v_pk_fma_f32 v[98:99], v[46:47], v[98:99], 1.0 op_sel_hi:[0,1,0]
	v_pk_mul_f32 v[42:43], v[42:43], v[98:99]
	v_pk_mul_f32 v[96:97], v[44:45], v[44:45]
	v_mul_f32_e32 v46, v188, v42
	v_mul_f32_e32 v46, v103, v46
	s_nop 1
	v_permlane32_swap_b32_e32 v187, v46
	v_add_f32_e32 v46, v187, v46
	v_mul_f32_e32 v98, v191, v43
	s_nop 0
	v_permlane16_swap_b32_e32 v201, v46
	v_mul_f32_e32 v98, v103, v98
	v_add_f32_e32 v46, v201, v46
	s_nop 0
	v_permlane32_swap_b32_e32 v186, v98
	v_add_f32_dpp v46, v46, v46 quad_perm:[1,0,3,2] row_mask:0xf bank_mask:0xf bound_ctrl:1
	v_add_f32_e32 v98, v186, v98
	s_nop 1
	v_permlane16_swap_b32_e32 v195, v98
	v_add_f32_dpp v46, v46, v46 quad_perm:[2,3,0,1] row_mask:0xf bank_mask:0xf bound_ctrl:1
	v_add_f32_e32 v98, v195, v98
	v_permlane32_swap_b32_e32 v198, v96
	v_add_f32_dpp v46, v46, v46 row_half_mirror row_mask:0xf bank_mask:0xf bound_ctrl:1
	v_permlane32_swap_b32_e32 v199, v97
	s_nop 0
	v_add_f32_dpp v46, v46, v46 row_mirror row_mask:0xf bank_mask:0xf bound_ctrl:1
	v_add_f32_dpp v98, v98, v98 quad_perm:[1,0,3,2] row_mask:0xf bank_mask:0xf bound_ctrl:1
	v_readlane_b32 s14, v46, 0
	v_readlane_b32 s64, v46, 16
	v_readlane_b32 s72, v46, 32
	v_readlane_b32 s96, v46, 48
	v_add_f32_e32 v46, v198, v96
	v_add_f32_e32 v96, v199, v97
	v_add_f32_dpp v98, v98, v98 quad_perm:[2,3,0,1] row_mask:0xf bank_mask:0xf bound_ctrl:1
	v_permlane16_swap_b32_e32 v196, v46
	v_permlane16_swap_b32_e32 v197, v96
	v_add_f32_dpp v98, v98, v98 row_half_mirror row_mask:0xf bank_mask:0xf bound_ctrl:1
	v_add_f32_e32 v46, v196, v46
	v_add_f32_e32 v96, v197, v96
	v_add_f32_dpp v98, v98, v98 row_mirror row_mask:0xf bank_mask:0xf bound_ctrl:1
	v_add_f32_dpp v46, v46, v46 quad_perm:[1,0,3,2] row_mask:0xf bank_mask:0xf bound_ctrl:1
	v_add_f32_dpp v96, v96, v96 quad_perm:[1,0,3,2] row_mask:0xf bank_mask:0xf bound_ctrl:1
	v_readlane_b32 s73, v98, 32
	v_add_f32_dpp v46, v46, v46 quad_perm:[2,3,0,1] row_mask:0xf bank_mask:0xf bound_ctrl:1
	v_add_f32_dpp v96, v96, v96 quad_perm:[2,3,0,1] row_mask:0xf bank_mask:0xf bound_ctrl:1
	v_readlane_b32 s15, v98, 0
	v_readlane_b32 s65, v98, 16
	v_readlane_b32 s97, v98, 48
	v_add_f32_dpp v46, v46, v46 row_half_mirror row_mask:0xf bank_mask:0xf bound_ctrl:1
	v_add_f32_dpp v96, v96, v96 row_half_mirror row_mask:0xf bank_mask:0xf bound_ctrl:1
	v_pk_mul_f32 v[196:197], v[84:85], s[72:73]
	s_lshl_b64 s[72:73], s[66:67], 13
	v_pk_mul_f32 v[98:99], v[36:37], s[14:15]
	v_pk_mul_f32 v[186:187], v[76:77], s[64:65]
	v_add_f32_dpp v46, v46, v46 row_mirror row_mask:0xf bank_mask:0xf bound_ctrl:1
	v_add_f32_dpp v96, v96, v96 row_mirror row_mask:0xf bank_mask:0xf bound_ctrl:1
	v_pk_mul_f32 v[198:199], v[92:93], s[96:97]
	v_readlane_b32 s15, v254, 39
	s_cmp_eq_u32 s68, 7
	v_readlane_b32 s93, v46, 0
	v_readlane_b32 s71, v46, 16
	v_readlane_b32 s69, v46, 32
	v_readlane_b32 s64, v46, 48
	v_readlane_b32 s14, v96, 0
	v_readlane_b32 s77, v96, 16
	v_readlane_b32 s70, v96, 32
	v_readlane_b32 s65, v96, 48
	v_add_u32_e32 v46, s15, v105
	v_cvt_pk_bf16_f32 v96, v98, v99
	v_cvt_pk_bf16_f32 v97, v186, v187
	v_cvt_pk_bf16_f32 v98, v196, v197
	v_cvt_pk_bf16_f32 v99, v198, v199
	v_lshl_add_u64 v[186:187], v[62:63], 0, s[72:73]
	s_cselect_b64 s[96:97], -1, 0
	ds_write_b32 v46, v52
	global_store_dwordx4 v[186:187], v[96:99], off
	s_and_b64 vcc, exec, s[96:97]
	s_nop 0
	v_cvt_pk_bf16_f32 v96, v47, v177
	v_cvt_pk_bf16_f32 v97, v182, v185
	v_cvt_pk_bf16_f32 v98, v189, v193
	s_waitcnt lgkmcnt(1)
	v_cvt_pk_bf16_f32 v99, v194, v200
	v_lshl_add_u64 v[46:47], v[64:65], 0, s[72:73]
	global_store_dwordx4 v[46:47], v[96:99], off
	s_cbranch_vccnz .LBB0_1416
	v_readlane_b32 s72, v254, 60
	s_lshl_b32 s94, s13, 7
	v_readlane_b32 s73, v254, 61
	v_lshl_add_u64 v[46:47], v[56:57], 0, s[94:95]
	s_andn2_b64 vcc, exec, s[72:73]
	s_cbranch_vccnz .LBB0_1415
	v_readlane_b32 s72, v254, 62
	v_readlane_b32 s73, v254, 63
	s_nop 1
	v_lshl_add_u64 v[96:97], v[46:47], 0, s[72:73]
	global_load_ushort v153, v[96:97], off
	global_load_ushort v202, v[96:97], off offset:1024
	global_load_ushort v215, v[96:97], off offset:2048
